# tile scheduler: second division replaced by shift/mask (group size is always 8); K-loop head aligned to 64 bytes
# speedup vs baseline: 1.0109x; 1.0031x over previous
;     __host__ __device__ bool next(int i, Unit& u) const {
;         const int nr = nwg / G; const long L = (long)((rev && nwg % G == 0) ? (i < nr ? nr - 1 - i : i) : i) * G + c; if (L >= nwg) return false;
;         int wgid = (int)L; { const int q = nwg / NXCD, r = nwg % NXCD, xcd = wgid % NXCD, off = wgid / NXCD; wgid = (xcd < r ? xcd * (q + 1) : r * (q + 1) + (xcd - r) * q) + off; }
;         const int nig = WGM * nN, gid = wgid / nig, fm = gid * WGM, gsz = (nM - fm) < WGM ? (nM - fm) : WGM;
;         u.pm = fm + ((wgid % nig) % gsz); u.pn = (wgid % nig) / gsz; return true;
.LBB0_511:
	s_mul_hi_i32 s7, s6, s52
	s_mul_i32 s6, s6, s52
	s_add_u32 s6, s6, s2
	s_addc_u32 s7, s7, s75
	v_mov_b64_e32 v[0:1], s[36:37]
	v_cmp_ge_i64_e32 vcc, s[6:7], v[0:1]
	v_cmp_lt_i64_e64 s[8:9], s[6:7], v[0:1]
	s_cbranch_vccnz .LBB0_513
	s_ashr_i32 s7, s6, 31
	s_lshr_b32 s7, s7, 29
	s_add_i32 s7, s6, s7
	s_ashr_i32 s12, s7, 3
	s_and_b32 s7, s7, -8
	s_sub_i32 s6, s6, s7
	s_lshr_b32 s7, s6, 31
	s_or_b32 s7, s50, s7
	s_mul_i32 s6, s7, s6
	s_add_i32 s6, s6, s12
	s_abs_i32 s12, s6
	s_mul_hi_u32 s13, s12, s59
	s_mul_i32 s14, s13, s56
	s_sub_i32 s12, s12, s14
	s_ashr_i32 s7, s6, 31
	s_add_i32 s14, s13, 1
	s_sub_i32 s15, s12, s56
	s_cmp_ge_u32 s12, s56
	s_cselect_b32 s13, s14, s13
	s_cselect_b32 s12, s15, s12
	s_add_i32 s14, s13, 1
	s_cmp_ge_u32 s12, s56
	s_cselect_b32 s12, s14, s13
	s_xor_b32 s12, s12, s7
	s_sub_i32 s7, s12, s7
	s_lshl_b32 s12, s7, 3
	s_mul_i32 s7, s7, s56
	s_sub_i32 s6, s6, s7
	s_lshr_b32 s39, s6, 3
	s_and_b32 s6, s6, 7
	s_add_i32 s48, s6, s12

; #define PG8_STAGE(bufoff, gbase, voff) do { _Pragma("unroll") for (int _i = 0; _i < 2; ++_i) \
;         __builtin_amdgcn_global_load_lds((const unsigned*)((const char*)(gbase) + (voff)[_i]), (PG8_LAS unsigned*)(lds + (bufoff) + ldsw + _i * 8192), 16, 0, 0); } while (0)
; #define PG8_LDA(dst, b, h) do { _Pragma("unroll") for (int m = 0; m < 4; ++m) _Pragma("unroll") for (int k = 0; k < 2; ++k) dst[m][k] = *(const PG8_LAS bf16x8*)(lds + PG8_SA(b, h) + aoff + m * 2048 + k * 1024); } while (0)
; #define PG8_LDB(dst, b, h) do { _Pragma("unroll") for (int n = 0; n < 2; ++n) _Pragma("unroll") for (int k = 0; k < 2; ++k) dst[n][k] = *(const PG8_LAS bf16x8*)(lds + PG8_SB(b, h) + boff + n * 2048 + k * 1024); } while (0)
; #define PG8_MMA(ai, bj, At, Bt) do { __builtin_amdgcn_s_setprio(1); _Pragma("unroll") for (int m = 0; m < 4; ++m) _Pragma("unroll") for (int n = 0; n < 2; ++n) _Pragma("unroll") for (int k = 0; k < 2; ++k) \
;         acc[ai][bj][m][n] = __builtin_amdgcn_mfma_f32_16x16x32_bf16(Bt[n][k], At[m][k], acc[ai][bj][m][n], 0, 0, 0); __builtin_amdgcn_s_setprio(0); } while (0)
; #define PG8_WAIT_V(n) asm volatile("s_waitcnt vmcnt(" #n ")" ::: "memory")
; #define PG8_WAIT_L(n) asm volatile("s_waitcnt lgkmcnt(" #n ")" ::: "memory")
; template <class Epi, class Sched, bool ALIGN_EPI = false, bool SP2 = false>
; __device__ __forceinline__ void gemm_phase(PG8_LAS unsigned char* lds, const Gemm g, const Sched& S, const Epi& E) {
;     ...
;             const bool last = (t == nt - 2);
;             const char* a1 = cA + (size_t)(t + 1) * kstep;
;             const char* a2 = last ? nA : cA + (size_t)(t + 2) * kstep; const char* b2 = last ? nB : cB + (size_t)(t + 2) * kstep;
;             const char* a3 = a2 + kstep; const char* b3 = b2 + kstep;
;             if (last && has_next) S.a_ready(nxt);
;             if constexpr (SP2) {
;             PG8_LDB(B0, 0, 0); PG8_LDB(B1, 0, 1); PG8_SCHED; PG8_LDA(At, 0, 0); PG8_STAGE(PG8_SA(1, 1), a1 + hstepA, voffA);
;             PG8_WAIT_V(8); PG8_WAIT_L(0); PG8_BAR; PG8_MMA(0, 0, At, B0); PG8_MMA(0, 1, At, B1); PG8_BAR; PG8_SCHED;
;             PG8_LDA(At, 0, 1); PG8_STAGE(PG8_SB(0, 0), b2, voffB); PG8_STAGE(PG8_SB(0, 1), b2 + hstepB, voffB); PG8_STAGE(PG8_SA(0, 0), a2, voffA);
;             PG8_WAIT_V(8); PG8_WAIT_L(0); PG8_BAR; PG8_MMA(1, 0, At, B0); PG8_MMA(1, 1, At, B1); PG8_BAR; PG8_SCHED;
.LBB0_517:
	s_add_u32 s0, s0, 0x80
	s_addc_u32 s1, s1, 0
	s_add_u32 s10, s10, 0x100
	s_addc_u32 s11, s11, 0
	s_mov_b32 s8, 0
	s_add_i32 s12, s8, 2
	s_add_u32 s13, s0, 0x80
	s_addc_u32 s9, s1, 0
	s_add_i32 s33, 0, 0x10000
	s_cmp_eq_u32 s95, s8
	s_cselect_b32 s9, s55, s9
	s_cselect_b32 s8, s54, s13
	s_cselect_b32 s15, s45, s11
	s_cselect_b32 s14, s44, s10
	s_add_i32 s13, 0, 0x14000
	v_add_u32_e32 v140, s33, v226
	v_add_u32_e32 v156, s13, v226
	s_waitcnt lgkmcnt(0)
	ds_read_b128 v[128:131], v140
	ds_read_b128 v[132:135], v140 offset:1024
	ds_read_b128 v[136:139], v140 offset:2048
	ds_read_b128 v[140:143], v140 offset:3072
	ds_read_b128 v[144:147], v156
	ds_read_b128 v[148:151], v156 offset:1024
	ds_read_b128 v[152:155], v156 offset:2048
	ds_read_b128 v[156:159], v156 offset:3072
	v_lshl_add_u64 v[212:213], s[0:1], 0, v[176:177]
	s_add_i32 m0, s79, 0xc000
	ds_read_b128 v[180:183], v227
	ds_read_b128 v[184:187], v227 offset:1024
	ds_read_b128 v[188:191], v227 offset:2048
	ds_read_b128 v[192:195], v227 offset:3072
	ds_read_b128 v[196:199], v227 offset:4096
	ds_read_b128 v[200:203], v227 offset:5120
	ds_read_b128 v[204:207], v227 offset:6144
	ds_read_b128 v[208:211], v227 offset:7168
	global_load_lds_dwordx4 v[212:213], off
	v_lshl_add_u64 v[212:213], s[0:1], 0, v[178:179]
	s_add_i32 m0, s79, 0xe000
	s_nop 0
	global_load_lds_dwordx4 v[212:213], off
	s_waitcnt vmcnt(8)
	s_waitcnt lgkmcnt(0)
	s_barrier
	s_setprio 1
	s_waitcnt lgkmcnt(0)
	v_mfma_f32_16x16x32_bf16 v[124:127], v[128:131], v[180:183], 0
	v_mfma_f32_16x16x32_bf16 v[120:123], v[136:139], v[180:183], 0
	v_mfma_f32_16x16x32_bf16 v[108:111], v[128:131], v[188:191], 0
	v_mfma_f32_16x16x32_bf16 v[104:107], v[136:139], v[188:191], 0
	v_mfma_f32_16x16x32_bf16 v[92:95], v[128:131], v[196:199], 0
	v_mfma_f32_16x16x32_bf16 v[88:91], v[136:139], v[196:199], 0
	v_mfma_f32_16x16x32_bf16 v[76:79], v[128:131], v[204:207], 0
	v_mfma_f32_16x16x32_bf16 v[72:75], v[136:139], v[204:207], 0
	v_mfma_f32_16x16x32_bf16 v[124:127], v[132:135], v[184:187], v[124:127]
	v_mfma_f32_16x16x32_bf16 v[120:123], v[140:143], v[184:187], v[120:123]
	v_mfma_f32_16x16x32_bf16 v[108:111], v[132:135], v[192:195], v[108:111]
	v_mfma_f32_16x16x32_bf16 v[104:107], v[140:143], v[192:195], v[104:107]
	v_mfma_f32_16x16x32_bf16 v[92:95], v[132:135], v[200:203], v[92:95]
	v_mfma_f32_16x16x32_bf16 v[88:91], v[140:143], v[200:203], v[88:91]
	v_mfma_f32_16x16x32_bf16 v[76:79], v[132:135], v[208:211], v[76:79]
	v_mfma_f32_16x16x32_bf16 v[72:75], v[140:143], v[208:211], v[72:75]
	s_setprio 0
	s_setprio 1
	v_mfma_f32_16x16x32_bf16 v[116:119], v[144:147], v[180:183], 0
	v_mfma_f32_16x16x32_bf16 v[112:115], v[152:155], v[180:183], 0
	v_mfma_f32_16x16x32_bf16 v[100:103], v[144:147], v[188:191], 0
	v_mfma_f32_16x16x32_bf16 v[96:99], v[152:155], v[188:191], 0
	v_mfma_f32_16x16x32_bf16 v[84:87], v[144:147], v[196:199], 0
	v_mfma_f32_16x16x32_bf16 v[80:83], v[152:155], v[196:199], 0
	v_mfma_f32_16x16x32_bf16 v[68:71], v[144:147], v[204:207], 0
	v_mfma_f32_16x16x32_bf16 v[64:67], v[152:155], v[204:207], 0
	v_mfma_f32_16x16x32_bf16 v[116:119], v[148:151], v[184:187], v[116:119]
	v_mfma_f32_16x16x32_bf16 v[112:115], v[156:159], v[184:187], v[112:115]
	v_mfma_f32_16x16x32_bf16 v[100:103], v[148:151], v[192:195], v[100:103]
	v_mfma_f32_16x16x32_bf16 v[96:99], v[156:159], v[192:195], v[96:99]
	v_mfma_f32_16x16x32_bf16 v[84:87], v[148:151], v[200:203], v[84:87]
	v_mfma_f32_16x16x32_bf16 v[80:83], v[156:159], v[200:203], v[80:83]
	v_mfma_f32_16x16x32_bf16 v[68:71], v[148:151], v[208:211], v[68:71]
	v_mfma_f32_16x16x32_bf16 v[64:67], v[156:159], v[208:211], v[64:67]
	s_setprio 0
	s_barrier
	s_add_i32 s33, s33, s78
	v_lshl_add_u64 v[212:213], s[14:15], 0, v[170:171]
	s_mov_b32 m0, s33
	ds_read_b128 v[180:183], v227 offset:16384
	ds_read_b128 v[184:187], v227 offset:17408
	ds_read_b128 v[188:191], v227 offset:18432
	ds_read_b128 v[192:195], v227 offset:19456
	ds_read_b128 v[196:199], v227 offset:20480
	ds_read_b128 v[200:203], v227 offset:21504
	ds_read_b128 v[204:207], v227 offset:22528
	ds_read_b128 v[208:211], v227 offset:23552
	global_load_lds_dwordx4 v[212:213], off
	s_add_i32 m0, s33, 0x2000
	v_lshl_add_u64 v[220:221], s[14:15], 0, v[174:175]
	s_add_u32 s14, s14, s38
	s_addc_u32 s15, s15, 0
	s_add_i32 s13, s13, s78
	global_load_lds_dwordx4 v[220:221], off
	v_lshl_add_u64 v[222:223], s[14:15], 0, v[170:171]
	s_mov_b32 m0, s13
	v_lshl_add_u64 v[228:229], s[14:15], 0, v[174:175]
	global_load_lds_dwordx4 v[222:223], off
	s_add_i32 m0, s13, 0x2000
	v_lshl_add_u64 v[230:231], s[8:9], 0, v[168:169]
	global_load_lds_dwordx4 v[228:229], off
	s_mov_b32 m0, s79
	v_lshl_add_u64 v[232:233], s[8:9], 0, v[172:173]
	global_load_lds_dwordx4 v[230:231], off
	s_mov_b32 m0, s82
	s_nop 0
	global_load_lds_dwordx4 v[232:233], off
	s_waitcnt vmcnt(8)
	s_waitcnt lgkmcnt(0)
	s_barrier
; #define PG8_STAGE(bufoff, gbase, voff) do { _Pragma("unroll") for (int _i = 0; _i < 2; ++_i) \
;         __builtin_amdgcn_global_load_lds((const unsigned*)((const char*)(gbase) + (voff)[_i]), (PG8_LAS unsigned*)(lds + (bufoff) + ldsw + _i * 8192), 16, 0, 0); } while (0)
; #define PG8_LDA(dst, b, h) do { _Pragma("unroll") for (int m = 0; m < 4; ++m) _Pragma("unroll") for (int k = 0; k < 2; ++k) dst[m][k] = *(const PG8_LAS bf16x8*)(lds + PG8_SA(b, h) + aoff + m * 2048 + k * 1024); } while (0)
; #define PG8_LDB(dst, b, h) do { _Pragma("unroll") for (int n = 0; n < 2; ++n) _Pragma("unroll") for (int k = 0; k < 2; ++k) dst[n][k] = *(const PG8_LAS bf16x8*)(lds + PG8_SB(b, h) + boff + n * 2048 + k * 1024); } while (0)
; #define PG8_MMA(ai, bj, At, Bt) do { __builtin_amdgcn_s_setprio(1); _Pragma("unroll") for (int m = 0; m < 4; ++m) _Pragma("unroll") for (int n = 0; n < 2; ++n) _Pragma("unroll") for (int k = 0; k < 2; ++k) \
;         acc[ai][bj][m][n] = __builtin_amdgcn_mfma_f32_16x16x32_bf16(Bt[n][k], At[m][k], acc[ai][bj][m][n], 0, 0, 0); __builtin_amdgcn_s_setprio(0); } while (0)
; #define PG8_WAIT_V(n) asm volatile("s_waitcnt vmcnt(" #n ")" ::: "memory")
; #define PG8_WAIT_L(n) asm volatile("s_waitcnt lgkmcnt(" #n ")" ::: "memory")
; #define PG8_BAR __builtin_amdgcn_s_barrier()
; #define PG8_SCHED __builtin_amdgcn_sched_barrier(0)
; template <class Epi, class Sched, bool ALIGN_EPI = false, bool SP2 = false>
; __device__ __forceinline__ void gemm_phase(PG8_LAS unsigned char* lds, const Gemm g, const Sched& S, const Epi& E) {
;     ...
;             PG8_WAIT_V(8); PG8_WAIT_L(0); PG8_BAR; PG8_MMA(1, 0, At, B0); PG8_MMA(1, 1, At, B1); PG8_BAR; PG8_SCHED;
;             PG8_LDB(B0, 1, 0); PG8_LDB(B1, 1, 1); PG8_SCHED; PG8_LDA(At, 1, 0); PG8_STAGE(PG8_SA(0, 1), a2 + hstepA, voffA);
;             PG8_WAIT_V(8); PG8_WAIT_L(0); PG8_BAR; PG8_MMA(0, 0, At, B0); PG8_MMA(0, 1, At, B1); PG8_BAR; PG8_SCHED;
;             PG8_LDA(At, 1, 1); PG8_STAGE(PG8_SB(1, 0), b3, voffB); PG8_STAGE(PG8_SB(1, 1), b3 + hstepB, voffB); PG8_STAGE(PG8_SA(1, 0), a3, voffA);
;             PG8_WAIT_V(8); PG8_WAIT_L(0); PG8_BAR; PG8_MMA(1, 0, At, B0); PG8_MMA(1, 1, At, B1); PG8_BAR; PG8_SCHED;
	s_setprio 1
	s_waitcnt lgkmcnt(0)
	v_mfma_f32_16x16x32_bf16 v[60:63], v[128:131], v[180:183], 0
	v_mfma_f32_16x16x32_bf16 v[56:59], v[136:139], v[180:183], 0
	v_mfma_f32_16x16x32_bf16 v[44:47], v[128:131], v[188:191], 0
	v_mfma_f32_16x16x32_bf16 v[40:43], v[136:139], v[188:191], 0
	v_mfma_f32_16x16x32_bf16 v[28:31], v[128:131], v[196:199], 0
	v_mfma_f32_16x16x32_bf16 v[24:27], v[136:139], v[196:199], 0
	v_mfma_f32_16x16x32_bf16 v[12:15], v[128:131], v[204:207], 0
	v_mfma_f32_16x16x32_bf16 v[8:11], v[136:139], v[204:207], 0
	v_mfma_f32_16x16x32_bf16 v[60:63], v[132:135], v[184:187], v[60:63]
	v_mfma_f32_16x16x32_bf16 v[56:59], v[140:143], v[184:187], v[56:59]
	v_mfma_f32_16x16x32_bf16 v[44:47], v[132:135], v[192:195], v[44:47]
	v_mfma_f32_16x16x32_bf16 v[40:43], v[140:143], v[192:195], v[40:43]
	v_mfma_f32_16x16x32_bf16 v[28:31], v[132:135], v[200:203], v[28:31]
	v_mfma_f32_16x16x32_bf16 v[24:27], v[140:143], v[200:203], v[24:27]
	v_mfma_f32_16x16x32_bf16 v[12:15], v[132:135], v[208:211], v[12:15]
	v_mfma_f32_16x16x32_bf16 v[8:11], v[140:143], v[208:211], v[8:11]
	s_setprio 0
	s_setprio 1
	v_mfma_f32_16x16x32_bf16 v[52:55], v[144:147], v[180:183], 0
	v_mfma_f32_16x16x32_bf16 v[48:51], v[152:155], v[180:183], 0
	v_mfma_f32_16x16x32_bf16 v[36:39], v[144:147], v[188:191], 0
	v_mfma_f32_16x16x32_bf16 v[32:35], v[152:155], v[188:191], 0
	v_mfma_f32_16x16x32_bf16 v[20:23], v[144:147], v[196:199], 0
	v_mfma_f32_16x16x32_bf16 v[16:19], v[152:155], v[196:199], 0
	v_mfma_f32_16x16x32_bf16 v[4:7], v[144:147], v[204:207], 0
	v_mfma_f32_16x16x32_bf16 v[0:3], v[152:155], v[204:207], 0
	v_mfma_f32_16x16x32_bf16 v[52:55], v[148:151], v[184:187], v[52:55]
	v_mfma_f32_16x16x32_bf16 v[48:51], v[156:159], v[184:187], v[48:51]
	v_mfma_f32_16x16x32_bf16 v[36:39], v[148:151], v[192:195], v[36:39]
	v_mfma_f32_16x16x32_bf16 v[32:35], v[156:159], v[192:195], v[32:35]
	v_mfma_f32_16x16x32_bf16 v[20:23], v[148:151], v[200:203], v[20:23]
	v_mfma_f32_16x16x32_bf16 v[16:19], v[156:159], v[200:203], v[16:19]
	v_mfma_f32_16x16x32_bf16 v[4:7], v[148:151], v[208:211], v[4:7]
	v_mfma_f32_16x16x32_bf16 v[0:3], v[156:159], v[208:211], v[0:3]
	s_setprio 0
	s_barrier
	s_add_i32 s13, 0, 0x18000
	s_add_i32 s14, 0, 0x1c000
	v_add_u32_e32 v140, s13, v226
	v_add_u32_e32 v156, s14, v226
	ds_read_b128 v[128:131], v140
	ds_read_b128 v[132:135], v140 offset:1024
	ds_read_b128 v[136:139], v140 offset:2048
	ds_read_b128 v[140:143], v140 offset:3072
	ds_read_b128 v[144:147], v156
	ds_read_b128 v[148:151], v156 offset:1024
	ds_read_b128 v[152:155], v156 offset:2048
	ds_read_b128 v[156:159], v156 offset:3072
	s_add_u32 s8, s8, s38
	s_addc_u32 s9, s9, 0
	s_mov_b32 m0, s83
	v_lshl_add_u64 v[234:235], s[8:9], 0, v[168:169]
	ds_read_b128 v[180:183], v227 offset:32768
	ds_read_b128 v[184:187], v227 offset:33792
	ds_read_b128 v[188:191], v227 offset:34816
	ds_read_b128 v[192:195], v227 offset:35840
	ds_read_b128 v[196:199], v227 offset:36864
	ds_read_b128 v[200:203], v227 offset:37888
	ds_read_b128 v[204:207], v227 offset:38912
	ds_read_b128 v[208:211], v227 offset:39936
	global_load_lds_dwordx4 v[234:235], off
	v_lshl_add_u64 v[234:235], s[8:9], 0, v[172:173]
	s_mov_b32 m0, s84
	s_nop 0
	global_load_lds_dwordx4 v[234:235], off
	s_waitcnt vmcnt(8)
	s_waitcnt lgkmcnt(0)
	s_barrier
	s_setprio 1
	s_waitcnt lgkmcnt(0)
	v_mfma_f32_16x16x32_bf16 v[124:127], v[128:131], v[180:183], v[124:127]
	v_mfma_f32_16x16x32_bf16 v[120:123], v[136:139], v[180:183], v[120:123]
	v_mfma_f32_16x16x32_bf16 v[108:111], v[128:131], v[188:191], v[108:111]
	v_mfma_f32_16x16x32_bf16 v[104:107], v[136:139], v[188:191], v[104:107]
	v_mfma_f32_16x16x32_bf16 v[92:95], v[128:131], v[196:199], v[92:95]
	v_mfma_f32_16x16x32_bf16 v[88:91], v[136:139], v[196:199], v[88:91]
	v_mfma_f32_16x16x32_bf16 v[76:79], v[128:131], v[204:207], v[76:79]
	v_mfma_f32_16x16x32_bf16 v[72:75], v[136:139], v[204:207], v[72:75]
	v_mfma_f32_16x16x32_bf16 v[124:127], v[132:135], v[184:187], v[124:127]
	v_mfma_f32_16x16x32_bf16 v[120:123], v[140:143], v[184:187], v[120:123]
	v_mfma_f32_16x16x32_bf16 v[108:111], v[132:135], v[192:195], v[108:111]
	v_mfma_f32_16x16x32_bf16 v[104:107], v[140:143], v[192:195], v[104:107]
	v_mfma_f32_16x16x32_bf16 v[92:95], v[132:135], v[200:203], v[92:95]
	v_mfma_f32_16x16x32_bf16 v[88:91], v[140:143], v[200:203], v[88:91]
	v_mfma_f32_16x16x32_bf16 v[76:79], v[132:135], v[208:211], v[76:79]
	v_mfma_f32_16x16x32_bf16 v[72:75], v[140:143], v[208:211], v[72:75]
	s_setprio 0
	s_setprio 1
	v_mfma_f32_16x16x32_bf16 v[116:119], v[144:147], v[180:183], v[116:119]
	v_mfma_f32_16x16x32_bf16 v[112:115], v[152:155], v[180:183], v[112:115]
	v_mfma_f32_16x16x32_bf16 v[100:103], v[144:147], v[188:191], v[100:103]
	v_mfma_f32_16x16x32_bf16 v[96:99], v[152:155], v[188:191], v[96:99]
	v_mfma_f32_16x16x32_bf16 v[84:87], v[144:147], v[196:199], v[84:87]
	v_mfma_f32_16x16x32_bf16 v[80:83], v[152:155], v[196:199], v[80:83]
	v_mfma_f32_16x16x32_bf16 v[68:71], v[144:147], v[204:207], v[68:71]
	v_mfma_f32_16x16x32_bf16 v[64:67], v[152:155], v[204:207], v[64:67]
	v_mfma_f32_16x16x32_bf16 v[116:119], v[148:151], v[184:187], v[116:119]
	v_mfma_f32_16x16x32_bf16 v[112:115], v[156:159], v[184:187], v[112:115]
	v_mfma_f32_16x16x32_bf16 v[100:103], v[148:151], v[192:195], v[100:103]
	v_mfma_f32_16x16x32_bf16 v[96:99], v[156:159], v[192:195], v[96:99]
	v_mfma_f32_16x16x32_bf16 v[84:87], v[148:151], v[200:203], v[84:87]
	v_mfma_f32_16x16x32_bf16 v[80:83], v[156:159], v[200:203], v[80:83]
	v_mfma_f32_16x16x32_bf16 v[68:71], v[148:151], v[208:211], v[68:71]
	v_mfma_f32_16x16x32_bf16 v[64:67], v[156:159], v[208:211], v[64:67]
	s_setprio 0
	s_barrier
; #define PG8_STAGE(bufoff, gbase, voff) do { _Pragma("unroll") for (int _i = 0; _i < 2; ++_i) \
;         __builtin_amdgcn_global_load_lds((const unsigned*)((const char*)(gbase) + (voff)[_i]), (PG8_LAS unsigned*)(lds + (bufoff) + ldsw + _i * 8192), 16, 0, 0); } while (0)
; #define PG8_LDA(dst, b, h) do { _Pragma("unroll") for (int m = 0; m < 4; ++m) _Pragma("unroll") for (int k = 0; k < 2; ++k) dst[m][k] = *(const PG8_LAS bf16x8*)(lds + PG8_SA(b, h) + aoff + m * 2048 + k * 1024); } while (0)
; #define PG8_LDB(dst, b, h) do { _Pragma("unroll") for (int n = 0; n < 2; ++n) _Pragma("unroll") for (int k = 0; k < 2; ++k) dst[n][k] = *(const PG8_LAS bf16x8*)(lds + PG8_SB(b, h) + boff + n * 2048 + k * 1024); } while (0)
; template <class Epi, class Sched, bool ALIGN_EPI = false, bool SP2 = false>
; __device__ __forceinline__ void gemm_phase(PG8_LAS unsigned char* lds, const Gemm g, const Sched& S, const Epi& E) {
;     ...
;         for (int t = 0; t < nt; t += 2) {
;             const bool last = (t == nt - 2);
;             const char* a1 = cA + (size_t)(t + 1) * kstep;
;             const char* a2 = last ? nA : cA + (size_t)(t + 2) * kstep; const char* b2 = last ? nB : cB + (size_t)(t + 2) * kstep;
;             const char* a3 = a2 + kstep; const char* b3 = b2 + kstep;
;             if (last && has_next) S.a_ready(nxt);
;             if constexpr (SP2) {
;             PG8_LDB(B0, 0, 0); PG8_LDB(B1, 0, 1); PG8_SCHED; PG8_LDA(At, 0, 0); PG8_STAGE(PG8_SA(1, 1), a1 + hstepA, voffA);
;             PG8_WAIT_V(8); PG8_WAIT_L(0); PG8_BAR; PG8_MMA(0, 0, At, B0); PG8_MMA(0, 1, At, B1); PG8_BAR; PG8_SCHED;
;             PG8_LDA(At, 0, 1); PG8_STAGE(PG8_SB(0, 0), b2, voffB); PG8_STAGE(PG8_SB(0, 1), b2 + hstepB, voffB); PG8_STAGE(PG8_SA(0, 0), a2, voffA);
;             PG8_WAIT_V(8); PG8_WAIT_L(0); PG8_BAR; PG8_MMA(1, 0, At, B0); PG8_MMA(1, 1, At, B1); PG8_BAR; PG8_SCHED;
;             PG8_LDB(B0, 1, 0); PG8_LDB(B1, 1, 1); PG8_SCHED; PG8_LDA(At, 1, 0); PG8_STAGE(PG8_SA(0, 1), a2 + hstepA, voffA);
;             PG8_WAIT_V(8); PG8_WAIT_L(0); PG8_BAR; PG8_MMA(0, 0, At, B0); PG8_MMA(0, 1, At, B1); PG8_BAR; PG8_SCHED;
;             PG8_LDA(At, 1, 1); PG8_STAGE(PG8_SB(1, 0), b3, voffB); PG8_STAGE(PG8_SB(1, 1), b3 + hstepB, voffB); PG8_STAGE(PG8_SA(1, 0), a3, voffA);
;             PG8_WAIT_V(8); PG8_WAIT_L(0); PG8_BAR; PG8_MMA(1, 0, At, B0); PG8_MMA(1, 1, At, B1); PG8_BAR; PG8_SCHED;
	s_add_i32 s8, s13, s78
	v_lshl_add_u64 v[212:213], v[212:213], 0, s[4:5]
	s_mov_b32 m0, s8
	ds_read_b128 v[180:183], v227 offset:49152
	ds_read_b128 v[184:187], v227 offset:50176
	ds_read_b128 v[188:191], v227 offset:51200
	ds_read_b128 v[192:195], v227 offset:52224
	ds_read_b128 v[196:199], v227 offset:53248
	ds_read_b128 v[200:203], v227 offset:54272
	ds_read_b128 v[204:207], v227 offset:55296
	ds_read_b128 v[208:211], v227 offset:56320
	global_load_lds_dwordx4 v[212:213], off
	v_lshl_add_u64 v[212:213], v[220:221], 0, s[4:5]
	s_add_i32 m0, s8, 0x2000
	s_add_i32 s8, s14, s78
	global_load_lds_dwordx4 v[212:213], off
	v_lshl_add_u64 v[212:213], v[222:223], 0, s[4:5]
	s_mov_b32 m0, s8
	s_nop 0
	global_load_lds_dwordx4 v[212:213], off
	v_lshl_add_u64 v[212:213], v[228:229], 0, s[4:5]
	s_add_i32 m0, s8, 0x2000
	s_nop 0
	global_load_lds_dwordx4 v[212:213], off
	v_lshl_add_u64 v[212:213], v[230:231], 0, s[4:5]
	s_mov_b32 m0, s91
	s_nop 0
	global_load_lds_dwordx4 v[212:213], off
	v_lshl_add_u64 v[212:213], v[232:233], 0, s[4:5]
	s_mov_b32 m0, s94
	s_nop 0
	global_load_lds_dwordx4 v[212:213], off
	s_waitcnt vmcnt(8)
	s_waitcnt lgkmcnt(0)
	s_barrier
	s_setprio 1
	s_waitcnt lgkmcnt(0)
	v_mfma_f32_16x16x32_bf16 v[60:63], v[128:131], v[180:183], v[60:63]
	v_mfma_f32_16x16x32_bf16 v[56:59], v[136:139], v[180:183], v[56:59]
	v_mfma_f32_16x16x32_bf16 v[44:47], v[128:131], v[188:191], v[44:47]
	v_mfma_f32_16x16x32_bf16 v[40:43], v[136:139], v[188:191], v[40:43]
	v_mfma_f32_16x16x32_bf16 v[28:31], v[128:131], v[196:199], v[28:31]
	v_mfma_f32_16x16x32_bf16 v[24:27], v[136:139], v[196:199], v[24:27]
	v_mfma_f32_16x16x32_bf16 v[12:15], v[128:131], v[204:207], v[12:15]
	v_mfma_f32_16x16x32_bf16 v[8:11], v[136:139], v[204:207], v[8:11]
	v_mfma_f32_16x16x32_bf16 v[60:63], v[132:135], v[184:187], v[60:63]
	v_mfma_f32_16x16x32_bf16 v[56:59], v[140:143], v[184:187], v[56:59]
	v_mfma_f32_16x16x32_bf16 v[44:47], v[132:135], v[192:195], v[44:47]
	v_mfma_f32_16x16x32_bf16 v[40:43], v[140:143], v[192:195], v[40:43]
	v_mfma_f32_16x16x32_bf16 v[28:31], v[132:135], v[200:203], v[28:31]
	v_mfma_f32_16x16x32_bf16 v[24:27], v[140:143], v[200:203], v[24:27]
	v_mfma_f32_16x16x32_bf16 v[12:15], v[132:135], v[208:211], v[12:15]
	v_mfma_f32_16x16x32_bf16 v[8:11], v[140:143], v[208:211], v[8:11]
	s_setprio 0
	s_setprio 1
	v_mfma_f32_16x16x32_bf16 v[52:55], v[144:147], v[180:183], v[52:55]
	v_mfma_f32_16x16x32_bf16 v[48:51], v[152:155], v[180:183], v[48:51]
	v_mfma_f32_16x16x32_bf16 v[36:39], v[144:147], v[188:191], v[36:39]
	v_mfma_f32_16x16x32_bf16 v[32:35], v[152:155], v[188:191], v[32:35]
	v_mfma_f32_16x16x32_bf16 v[20:23], v[144:147], v[196:199], v[20:23]
	v_mfma_f32_16x16x32_bf16 v[16:19], v[152:155], v[196:199], v[16:19]
	v_mfma_f32_16x16x32_bf16 v[4:7], v[144:147], v[204:207], v[4:7]
	v_mfma_f32_16x16x32_bf16 v[0:3], v[152:155], v[204:207], v[0:3]
	v_mfma_f32_16x16x32_bf16 v[52:55], v[148:151], v[184:187], v[52:55]
	v_mfma_f32_16x16x32_bf16 v[48:51], v[156:159], v[184:187], v[48:51]
	v_mfma_f32_16x16x32_bf16 v[36:39], v[148:151], v[192:195], v[36:39]
	v_mfma_f32_16x16x32_bf16 v[32:35], v[156:159], v[192:195], v[32:35]
	v_mfma_f32_16x16x32_bf16 v[20:23], v[148:151], v[200:203], v[20:23]
	v_mfma_f32_16x16x32_bf16 v[16:19], v[156:159], v[200:203], v[16:19]
	v_mfma_f32_16x16x32_bf16 v[4:7], v[148:151], v[208:211], v[4:7]
	v_mfma_f32_16x16x32_bf16 v[0:3], v[156:159], v[208:211], v[0:3]
	s_setprio 0
	s_barrier
	s_add_u32 s0, s0, 0x100
	s_addc_u32 s1, s1, 0
	s_add_u32 s10, s10, 0x100
	s_addc_u32 s11, s11, 0
	s_cmp_ge_u32 s12, s86
	s_mov_b32 s8, s12
	s_cbranch_scc1 .Lkloop_done
	.p2align	6
